# v83 + P6 leftover late weight copies taken by all workgroups (GLU-side WGs pull from the late queue too)
# baseline (speedup 1.0000x reference)
.LBB0_977:
	s_cmpk_gt_i32 s2, 0xffff
	s_cselect_b64 s[4:5], -1, 0
	s_and_b64 s[4:5], s[4:5], s[48:49]
	s_and_b64 vcc, exec, s[4:5]
	s_cbranch_vccz .LBB0_1060
	s_mov_b64 s[4:5], s[0:1]
	s_load_dwordx2 s[6:7], s[4:5], 0xe0
	v_mov_b32_e32 v1, v0
	s_waitcnt lgkmcnt(0)
	s_add_u32 s16, s6, 0xa000
	s_addc_u32 s17, s7, 0
	v_cmp_eq_u32_e32 vcc, 0, v1
	s_and_saveexec_b64 s[4:5], vcc
	s_cbranch_execz .LBB0_982
	s_mov_b64 s[10:11], exec
	v_mbcnt_lo_u32_b32 v2, s10, 0
	v_mbcnt_hi_u32_b32 v2, s11, v2
	v_cmp_eq_u32_e32 vcc, 0, v2
	s_and_saveexec_b64 s[8:9], vcc
	s_cbranch_execz .LBB0_981
	s_bcnt1_i32_b64 s10, s[10:11]
	v_mov_b32_e32 v3, 0
	v_mov_b32_e32 v4, s10
	global_atomic_add v3, v3, v4, s[16:17] sc0
